# attention O epilogue staged through wave-private LDS and stored as whole 256-byte rows (8 dwordx4 per wave, 4 rows each)
# baseline (speedup 1.0000x reference)
; __device__ __forceinline__ unsigned cvtpk(float lo, float hi) { return pg8::cvt_pk_bf16(lo, hi); }
; __device__ __forceinline__ void attn_phase(const Params& p, LAS unsigned char* lds) {
;     ...
;             __syncthreads();
;             const float ltot = lrun + __shfl_xor(lrun, 32), inv = 1.0f / ltot;
;             bf16* orow = AO + rowq * 1024 + h * 128;
; #pragma unroll
;             for (int d = 0; d < 4; ++d)
; #pragma unroll
;                 for (int g = 0; g < 4; ++g)
;                     *(u32x2*)(orow + d * 32 + 8 * g + 4 * hi) = (u32x2){cvtpk(o[d][4 * g] * inv, o[d][4 * g + 1] * inv), cvtpk(o[d][4 * g + 2] * inv, o[d][4 * g + 3] * inv)};
.LBB0_636:
	ds_bpermute_b32 v64, v241, v84
	s_waitcnt lgkmcnt(0)
	s_barrier
	v_add_f32_e32 v64, v84, v64
	v_div_scale_f32 v65, s[44:45], v64, v64, 1.0
	v_rcp_f32_e32 v66, v65
	v_div_scale_f32 v67, vcc, 1.0, v64, 1.0
	s_mov_b64 s[44:45], 0
	v_fma_f32 v68, -v65, v66, 1.0
	v_fmac_f32_e32 v66, v68, v66
	v_mul_f32_e32 v68, v67, v66
	v_fma_f32 v69, -v65, v68, v67
	v_fmac_f32_e32 v68, v69, v66
	v_fma_f32 v65, -v65, v68, v67
	v_div_fmas_f32 v65, v65, v66, v68
	v_div_fixup_f32 v64, v65, v64, 1.0
	v_lshl_add_u64 v[66:67], v[210:211], 0, v[226:227]
	v_mbcnt_lo_u32_b32 v68, -1, 0
	v_mbcnt_hi_u32_b32 v68, -1, v68
	v_readfirstlane_b32 s70, v66
	v_readfirstlane_b32 s71, v67
	v_readfirstlane_b32 s72, v201
	v_and_b32_e32 v69, 31, v68
	v_lshrrev_b32_e32 v70, 5, v68
	v_lshrrev_b32_e32 v71, 4, v68
	v_and_b32_e32 v72, 15, v68
	s_lshr_b32 s72, s72, 6
	s_mul_i32 s72, s72, 0x2200
	s_add_i32 s72, s72, 0xb400
	v_mul_u32_u24_e32 v69, 0x110, v69
	v_lshl_add_u32 v69, v70, 3, v69
	v_add_u32_e32 v69, s72, v69
	v_mul_u32_u24_e32 v73, 0x110, v71
	v_lshl_add_u32 v73, v72, 4, v73
	v_add_u32_e32 v73, s72, v73
	v_lshlrev_b32_e32 v74, 11, v71
	v_lshl_add_u32 v74, v72, 4, v74
	v_mul_f32_e32 v48, v48, v64
	v_mul_f32_e32 v49, v49, v64
	v_mul_f32_e32 v50, v50, v64
	v_mul_f32_e32 v51, v51, v64
	v_mul_f32_e32 v52, v52, v64
	v_mul_f32_e32 v53, v53, v64
	v_mul_f32_e32 v54, v54, v64
	v_mul_f32_e32 v55, v55, v64
	v_cvt_pk_bf16_f32 v48, v48, v49
	v_cvt_pk_bf16_f32 v49, v50, v51
	v_cvt_pk_bf16_f32 v50, v52, v53
	v_cvt_pk_bf16_f32 v51, v54, v55
	ds_write_b64 v69, v[48:49] offset:0
	ds_write_b64 v69, v[50:51] offset:16
	v_mul_f32_e32 v56, v56, v64
	v_mul_f32_e32 v57, v57, v64
	v_mul_f32_e32 v58, v58, v64
	v_mul_f32_e32 v59, v59, v64
	v_mul_f32_e32 v60, v60, v64
	v_mul_f32_e32 v61, v61, v64
	v_mul_f32_e32 v62, v62, v64
	v_mul_f32_e32 v63, v63, v64
	v_cvt_pk_bf16_f32 v56, v56, v57
	v_cvt_pk_bf16_f32 v57, v58, v59
	v_cvt_pk_bf16_f32 v58, v60, v61
	v_cvt_pk_bf16_f32 v59, v62, v63
	ds_write_b64 v69, v[56:57] offset:32
	ds_write_b64 v69, v[58:59] offset:48
	v_mul_f32_e32 v32, v32, v64
	v_mul_f32_e32 v33, v33, v64
	v_mul_f32_e32 v34, v34, v64
	v_mul_f32_e32 v35, v35, v64
	v_mul_f32_e32 v36, v36, v64
	v_mul_f32_e32 v37, v37, v64
	v_mul_f32_e32 v38, v38, v64
	v_mul_f32_e32 v39, v39, v64
	v_cvt_pk_bf16_f32 v32, v32, v33
	v_cvt_pk_bf16_f32 v33, v34, v35
	v_cvt_pk_bf16_f32 v34, v36, v37
	v_cvt_pk_bf16_f32 v35, v38, v39
	ds_write_b64 v69, v[32:33] offset:64
	ds_write_b64 v69, v[34:35] offset:80
	v_mul_f32_e32 v40, v40, v64
	v_mul_f32_e32 v41, v41, v64
	v_mul_f32_e32 v42, v42, v64
	v_mul_f32_e32 v43, v43, v64
	v_mul_f32_e32 v44, v44, v64
	v_mul_f32_e32 v45, v45, v64
	v_mul_f32_e32 v46, v46, v64
	v_mul_f32_e32 v47, v47, v64
	v_cvt_pk_bf16_f32 v40, v40, v41
	v_cvt_pk_bf16_f32 v41, v42, v43
	v_cvt_pk_bf16_f32 v42, v44, v45
	v_cvt_pk_bf16_f32 v43, v46, v47
	ds_write_b64 v69, v[40:41] offset:96
	ds_write_b64 v69, v[42:43] offset:112
	v_mul_f32_e32 v16, v16, v64
	v_mul_f32_e32 v17, v17, v64
	v_mul_f32_e32 v18, v18, v64
	v_mul_f32_e32 v19, v19, v64
	v_mul_f32_e32 v20, v20, v64
	v_mul_f32_e32 v21, v21, v64
	v_mul_f32_e32 v22, v22, v64
	v_mul_f32_e32 v23, v23, v64
	v_cvt_pk_bf16_f32 v16, v16, v17
	v_cvt_pk_bf16_f32 v17, v18, v19
	v_cvt_pk_bf16_f32 v18, v20, v21
	v_cvt_pk_bf16_f32 v19, v22, v23
	ds_write_b64 v69, v[16:17] offset:128
	ds_write_b64 v69, v[18:19] offset:144
	v_mul_f32_e32 v24, v24, v64
	v_mul_f32_e32 v25, v25, v64
	v_mul_f32_e32 v26, v26, v64
	v_mul_f32_e32 v27, v27, v64
	v_mul_f32_e32 v28, v28, v64
	v_mul_f32_e32 v29, v29, v64
	v_mul_f32_e32 v30, v30, v64
	v_mul_f32_e32 v31, v31, v64
	v_cvt_pk_bf16_f32 v24, v24, v25
	v_cvt_pk_bf16_f32 v25, v26, v27
	v_cvt_pk_bf16_f32 v26, v28, v29
	v_cvt_pk_bf16_f32 v27, v30, v31
	ds_write_b64 v69, v[24:25] offset:160
	ds_write_b64 v69, v[26:27] offset:176
	v_mul_f32_e32 v0, v0, v64
	v_mul_f32_e32 v1, v1, v64
	v_mul_f32_e32 v2, v2, v64
	v_mul_f32_e32 v3, v3, v64
	v_mul_f32_e32 v4, v4, v64
	v_mul_f32_e32 v5, v5, v64
	v_mul_f32_e32 v6, v6, v64
	v_mul_f32_e32 v7, v7, v64
	v_cvt_pk_bf16_f32 v0, v0, v1
	v_cvt_pk_bf16_f32 v1, v2, v3
	v_cvt_pk_bf16_f32 v2, v4, v5
	v_cvt_pk_bf16_f32 v3, v6, v7
	ds_write_b64 v69, v[0:1] offset:192
	ds_write_b64 v69, v[2:3] offset:208
	v_mul_f32_e32 v8, v8, v64
	v_mul_f32_e32 v9, v9, v64
	v_mul_f32_e32 v10, v10, v64
	v_mul_f32_e32 v11, v11, v64
	v_mul_f32_e32 v12, v12, v64
	v_mul_f32_e32 v13, v13, v64
	v_mul_f32_e32 v14, v14, v64
	v_mul_f32_e32 v15, v15, v64
	v_cvt_pk_bf16_f32 v8, v8, v9
	v_cvt_pk_bf16_f32 v9, v10, v11
	v_cvt_pk_bf16_f32 v10, v12, v13
	v_cvt_pk_bf16_f32 v11, v14, v15
	ds_write_b64 v69, v[8:9] offset:224
	ds_write_b64 v69, v[10:11] offset:240
	s_waitcnt lgkmcnt(0)
	ds_read_b128 v[96:99], v73
	ds_read_b128 v[100:103], v73 offset:1088
	ds_read_b128 v[104:107], v73 offset:2176
	ds_read_b128 v[108:111], v73 offset:3264
	ds_read_b128 v[112:115], v73 offset:4352
	ds_read_b128 v[116:119], v73 offset:5440
	ds_read_b128 v[120:123], v73 offset:6528
	ds_read_b128 v[124:127], v73 offset:7616
	s_waitcnt lgkmcnt(7)
	global_store_dwordx4 v74, v[96:99], s[70:71]
	s_add_u32 s70, s70, 0x2000
	s_addc_u32 s71, s71, 0
	s_waitcnt lgkmcnt(6)
	global_store_dwordx4 v74, v[100:103], s[70:71]
	s_add_u32 s70, s70, 0x2000
	s_addc_u32 s71, s71, 0
	s_waitcnt lgkmcnt(5)
	global_store_dwordx4 v74, v[104:107], s[70:71]
	s_add_u32 s70, s70, 0x2000
	s_addc_u32 s71, s71, 0
	s_waitcnt lgkmcnt(4)
	global_store_dwordx4 v74, v[108:111], s[70:71]
	s_add_u32 s70, s70, 0x2000
	s_addc_u32 s71, s71, 0
	s_waitcnt lgkmcnt(3)
	global_store_dwordx4 v74, v[112:115], s[70:71]
	s_add_u32 s70, s70, 0x2000
	s_addc_u32 s71, s71, 0
	s_waitcnt lgkmcnt(2)
	global_store_dwordx4 v74, v[116:119], s[70:71]
	s_add_u32 s70, s70, 0x2000
	s_addc_u32 s71, s71, 0
	s_waitcnt lgkmcnt(1)
	global_store_dwordx4 v74, v[120:123], s[70:71]
	s_add_u32 s70, s70, 0x2000
	s_addc_u32 s71, s71, 0
	s_waitcnt lgkmcnt(0)
	global_store_dwordx4 v74, v[124:127], s[70:71]
	s_and_b64 vcc, exec, s[42:43]
	s_nop 1
	s_cbranch_vccnz .LBB0_634
